# intra-wave movement without LDS: cross-half row-max exchange via v_permlane32_swap instead of ds_bpermute+lgkm wait in fox/CMP/SLC/WIN loops
# speedup vs baseline: 1.0036x; 1.0036x over previous
; template <int MODE> ...
;     ...
;           if (domask) {
; #pragma unroll
;             for (int i = 0; i < 16; ++i) {
;               const int kk = kbase + (i & 3) + 8 * (i >> 2) + 4 * h;
;               bool valid;
;               if (MODE == M_FOX) valid = (kk <= t);
;               else if (MODE == M_CMP || MODE == M_CMP2) valid = (16 * kk + 31 <= t) && (kk < 255);
;               else if (MODE == M_SLC) valid = sb && (kk <= t);
;               else valid = (kk <= t) && (kk > t - 512);
;               sv[i] = valid ? Sn[i] : -INFINITY;
;             }
;           } else {
; #pragma unroll
;             for (int i = 0; i < 16; ++i) sv[i] = (MODE == M_SLC) ? (sb ? Sn[i] : -INFINITY) : Sn[i];
;           }
;           if (MODE == M_CMP2) {
; #pragma unroll
;             for (int a4 = 0; a4 < 4; ++a4) {
;               float pe[4];
; #pragma unroll
;               for (int e = 0; e < 4; ++e) pe[e] = __builtin_amdgcn_exp2f(sv[4 * a4 + e] - m[nb]) * linv[nb];
;               mainv[nb][a4] = pe[0] + pe[1] + pe[2] + 0.5f * pe[3];
;               spill[nb][a4] = 0.5f * pe[3];
;             }
;           } else {
;             float mx = sv[0];
; #pragma unroll
;             for (int i = 1; i < 16; ++i) mx = fmaxf(mx, sv[i]);
;             mx = fmaxf(mx, shx(mx, lane, 32));
;             if (__any(mx > m[nb] + 8.f)) {
;               const float mnew = (mx > m[nb] + 8.f) ? mx : m[nb];
;               const float alpha = __builtin_amdgcn_exp2f(m[nb] - mnew);
;               m[nb] = mnew;
;               l[nb] *= alpha;
; #pragma unroll
;               for (int i = 0; i < 16; ++i) { O[0][nb][i] *= alpha; O[1][nb][i] *= alpha; }
;             }
.LBB0_652:
	s_or_b64 exec, exec, s[14:15]
	s_nop 1
	v_max_f32_e32 v2, v113, v113
	v_max_f32_e32 v3, v112, v112
	v_max_f32_e32 v2, v3, v2
	v_max3_f32 v2, v2, v114, v115
	v_max3_f32 v2, v2, v116, v117
	v_max3_f32 v2, v2, v118, v119
	v_max3_f32 v2, v2, v120, v121
	v_max3_f32 v2, v2, v122, v123
	v_max3_f32 v2, v2, v124, v125
	v_max3_f32 v2, v2, v126, v127
	v_mov_b32_e32 v3, v2
	s_nop 1
	v_permlane32_swap_b32 v2, v3
	s_and_saveexec_b64 s[14:15], s[0:1]
	s_cbranch_execz .LBB0_656
	v_cmp_le_i32_e32 vcc, v213, v233
	s_nop 8
	v_cndmask_b32_e32 v128, v227, v128, vcc
	v_cmp_lt_i32_e32 vcc, v213, v233
	s_nop 1
	v_cndmask_b32_e32 v129, v227, v129, vcc
	v_cmp_le_i32_e32 vcc, v213, v247
	s_nop 1
	v_cndmask_b32_e32 v130, v227, v130, vcc
	v_cmp_le_i32_e32 vcc, v213, v248
	s_nop 1
	v_cndmask_b32_e32 v131, v227, v131, vcc
	v_cmp_le_i32_e32 vcc, v213, v249
	s_nop 1
	v_cndmask_b32_e32 v132, v227, v132, vcc
	v_cmp_le_i32_e32 vcc, v213, v250
	s_nop 1
	v_cndmask_b32_e32 v133, v227, v133, vcc
	v_cmp_le_i32_e32 vcc, v213, v218
	s_nop 1
	v_cndmask_b32_e32 v134, v227, v134, vcc
	v_cmp_le_i32_e32 vcc, v213, v216
	s_nop 1
	v_cndmask_b32_e32 v135, v227, v135, vcc
	v_cmp_le_i32_e32 vcc, v213, v217
	s_nop 1
	v_cndmask_b32_e32 v136, v227, v136, vcc
	v_cmp_le_i32_e32 vcc, v213, v228
	s_nop 1
	v_cndmask_b32_e32 v137, v227, v137, vcc
	v_cmp_le_i32_e32 vcc, v213, v229
	s_nop 1
	v_cndmask_b32_e32 v138, v227, v138, vcc
	v_cmp_le_i32_e32 vcc, v213, v230
	s_nop 1
	v_cndmask_b32_e32 v139, v227, v139, vcc
	v_cmp_le_i32_e32 vcc, v213, v231
	s_nop 1
	v_cndmask_b32_e32 v140, v227, v140, vcc
	v_cmp_le_i32_e32 vcc, v213, v223
	s_nop 1
	v_cndmask_b32_e32 v141, v227, v141, vcc
	v_cmp_le_i32_e32 vcc, v213, v226
	s_nop 1
	v_cndmask_b32_e32 v142, v227, v142, vcc
	v_cmp_le_i32_e32 vcc, v213, v221
	s_nop 1
	v_cndmask_b32_e32 v143, v227, v143, vcc
.LBB0_656:
	s_or_b64 exec, exec, s[14:15]
	s_nop 1
	v_max_f32_e32 v4, v129, v129
	v_max_f32_e32 v5, v128, v128
	v_max_f32_e32 v4, v5, v4
	v_max3_f32 v4, v4, v130, v131
	v_max3_f32 v4, v4, v132, v133
	v_max3_f32 v4, v4, v134, v135
	v_max3_f32 v4, v4, v136, v137
	v_max3_f32 v4, v4, v138, v139
	v_max3_f32 v4, v4, v140, v141
	v_max3_f32 v4, v4, v142, v143
	v_mov_b32_e32 v5, v4
	s_nop 1
	v_permlane32_swap_b32 v4, v5
	s_waitcnt lgkmcnt(1)
	v_max_f32_e32 v3, v3, v3
	v_max_f32_e32 v2, v2, v3
	v_add_f32_e32 v3, 0x41000000, v219
	v_cmp_gt_f32_e32 vcc, v2, v3
	s_cbranch_vccz .LBB0_654
	s_nop 0
	v_cndmask_b32_e32 v3, v219, v2, vcc
	v_sub_f32_e32 v2, v219, v3
	v_exp_f32_e32 v2, v2
	v_mov_b32_e32 v219, v3
	v_mul_f32_e32 v208, v208, v2
	v_pk_mul_f32 v[78:79], v[78:79], v[2:3] op_sel_hi:[1,0]
	v_pk_mul_f32 v[76:77], v[76:77], v[2:3] op_sel_hi:[1,0]
	v_pk_mul_f32 v[74:75], v[74:75], v[2:3] op_sel_hi:[1,0]
	v_pk_mul_f32 v[72:73], v[72:73], v[2:3] op_sel_hi:[1,0]
	v_pk_mul_f32 v[70:71], v[70:71], v[2:3] op_sel_hi:[1,0]
	v_pk_mul_f32 v[68:69], v[68:69], v[2:3] op_sel_hi:[1,0]
	v_pk_mul_f32 v[66:67], v[66:67], v[2:3] op_sel_hi:[1,0]
	v_pk_mul_f32 v[64:65], v[64:65], v[2:3] op_sel_hi:[1,0]
	v_pk_mul_f32 v[62:63], v[62:63], v[2:3] op_sel_hi:[1,0]
	v_pk_mul_f32 v[60:61], v[60:61], v[2:3] op_sel_hi:[1,0]
	v_pk_mul_f32 v[58:59], v[58:59], v[2:3] op_sel_hi:[1,0]
	v_pk_mul_f32 v[56:57], v[56:57], v[2:3] op_sel_hi:[1,0]
	v_pk_mul_f32 v[54:55], v[54:55], v[2:3] op_sel_hi:[1,0]
	v_pk_mul_f32 v[52:53], v[52:53], v[2:3] op_sel_hi:[1,0]
	v_pk_mul_f32 v[50:51], v[50:51], v[2:3] op_sel_hi:[1,0]
	v_pk_mul_f32 v[48:49], v[48:49], v[2:3] op_sel_hi:[1,0]

; #define MFMA(a, b, c) __builtin_amdgcn_mfma_f32_32x32x16_f16(__builtin_bit_cast(h16x8, (a)), __builtin_bit_cast(h16x8, (b)), (c), 0, 0, 0)
; template <int MODE> ...
;     ...
; #pragma unroll
;           for (int ks = 0; ks < 4; ++ks) {
;             const bf16x8 a = *(const bf16x8*)(Kt + (kb * 32 + r) * LDK + ks * 16 + 8 * h);
;             Sn = MFMA(a, qf[nb][ks], Sn);
;           }
;           float sv[16];
;           const int t = qpos[nb];
;           bool sb = true;
;           if (MODE == M_SLC) sb = (((selb[nb] >> (key0 >> 6)) & 1ull) != 0ull);
;           if (domask) {
; #pragma unroll
;             for (int i = 0; i < 16; ++i) {
;               const int kk = kbase + (i & 3) + 8 * (i >> 2) + 4 * h;
;               bool valid;
;               if (MODE == M_FOX) valid = (kk <= t);
;               else if (MODE == M_CMP || MODE == M_CMP2) valid = (16 * kk + 31 <= t) && (kk < 255);
;               else if (MODE == M_SLC) valid = sb && (kk <= t);
;               else valid = (kk <= t) && (kk > t - 512);
;               sv[i] = valid ? Sn[i] : -INFINITY;
;             }
;           } else {
; #pragma unroll
;             for (int i = 0; i < 16; ++i) sv[i] = (MODE == M_SLC) ? (sb ? Sn[i] : -INFINITY) : Sn[i];
;           }
;           if (MODE == M_CMP2) {
; #pragma unroll
;             for (int a4 = 0; a4 < 4; ++a4) {
;               float pe[4];
; #pragma unroll
;               for (int e = 0; e < 4; ++e) pe[e] = __builtin_amdgcn_exp2f(sv[4 * a4 + e] - m[nb]) * linv[nb];
;               mainv[nb][a4] = pe[0] + pe[1] + pe[2] + 0.5f * pe[3];
;               spill[nb][a4] = 0.5f * pe[3];
;             }
;           } else {
;             float mx = sv[0];
; #pragma unroll
;             for (int i = 1; i < 16; ++i) mx = fmaxf(mx, sv[i]);
;             mx = fmaxf(mx, shx(mx, lane, 32));
;             if (__any(mx > m[nb] + 8.f)) {
;               const float mnew = (mx > m[nb] + 8.f) ? mx : m[nb];
;               const float alpha = __builtin_amdgcn_exp2f(m[nb] - mnew);
;               m[nb] = mnew;
;               l[nb] *= alpha;
; #pragma unroll
;               for (int i = 0; i < 16; ++i) { O[0][nb][i] *= alpha; O[1][nb][i] *= alpha; }
;             }
.LBB0_675:
	s_or_b32 s0, s46, s45
	s_lshl_b32 s1, s0, 4
	s_cmp_gt_u32 s1, s43
	s_cbranch_scc1 .LBB0_674
	v_or_b32_e32 v2, s46, v151
	v_mad_u32_u24 v144, v2, s76, v0
	ds_read_b128 v[2:5], v144
	ds_read_b128 v[6:9], v144 offset:32
	ds_read_b128 v[10:13], v144 offset:64
	ds_read_b128 v[144:147], v144 offset:96
	v_or_b32_e32 v175, s0, v163
	v_lshl_or_b32 v195, v175, 4, 31
	v_or_b32_e32 v170, 1, v175
	v_cmp_gt_u32_e64 s[14:15], s33, v175
	v_or_b32_e32 v171, 2, v175
	v_cmp_le_i32_e32 vcc, v195, v178
	s_waitcnt lgkmcnt(3)
	v_mfma_f32_32x32x16_f16 v[80:95], v[2:5], v[120:123], 0
	v_lshl_add_u32 v205, v170, 4, 31
	v_or_b32_e32 v174, 3, v175
	v_cmp_gt_u32_e64 s[28:29], s33, v170
	v_lshl_or_b32 v202, v171, 4, 31
	v_cmp_le_i32_e64 s[0:1], v205, v178
	s_and_b64 vcc, vcc, s[14:15]
	v_or_b32_e32 v176, 8, v175
	s_waitcnt lgkmcnt(2)
	v_mfma_f32_32x32x16_f16 v[80:95], v[6:9], v[112:115], v[80:95]
	v_cmp_gt_u32_e64 s[22:23], s33, v171
	v_lshl_add_u32 v200, v174, 4, 31
	v_cmp_le_i32_e64 s[2:3], v202, v178
	v_or_b32_e32 v180, 9, v175
	v_cmp_gt_u32_e64 s[20:21], s33, v174
	v_lshl_or_b32 v199, v176, 4, 31
	v_cmp_le_i32_e64 s[4:5], v200, v178
	s_waitcnt lgkmcnt(1)
	v_mfma_f32_32x32x16_f16 v[80:95], v[10:13], v[116:119], v[80:95]
	v_cmp_gt_u32_e64 s[18:19], s33, v176
	v_lshl_add_u32 v198, v180, 4, 31
	v_cmp_le_i32_e64 s[6:7], v199, v178
	v_cmp_gt_u32_e64 s[16:17], s33, v180
	v_cmp_le_i32_e64 s[8:9], v198, v178
	s_waitcnt lgkmcnt(0)
	v_mfma_f32_32x32x16_f16 v[80:95], v[144:147], v[124:127], v[80:95]
	s_nop 11
	v_cndmask_b32_e32 v190, v227, v80, vcc
	s_and_b64 vcc, s[0:1], s[28:29]
	v_cndmask_b32_e32 v189, v227, v81, vcc
	s_and_b64 vcc, s[2:3], s[22:23]
	v_cndmask_b32_e32 v188, v227, v82, vcc
	s_and_b64 vcc, s[4:5], s[20:21]
	v_cndmask_b32_e32 v187, v227, v83, vcc
	s_and_b64 vcc, s[6:7], s[18:19]
	v_or_b32_e32 v80, 10, v175
	v_cndmask_b32_e32 v186, v227, v84, vcc
	s_and_b64 vcc, s[8:9], s[16:17]
	v_lshl_or_b32 v206, v80, 4, 31
	v_cndmask_b32_e32 v183, v227, v85, vcc
	v_cmp_le_i32_e32 vcc, v206, v178
	v_cmp_gt_u32_e64 s[30:31], s33, v80
	v_or_b32_e32 v80, 11, v175
	s_and_b64 vcc, vcc, s[30:31]
	v_lshl_add_u32 v204, v80, 4, 31
	v_cndmask_b32_e32 v184, v227, v86, vcc
	v_cmp_le_i32_e32 vcc, v204, v178
	v_cmp_gt_u32_e64 s[26:27], s33, v80
	v_or_b32_e32 v80, 16, v175
	s_and_b64 vcc, vcc, s[26:27]
	v_lshl_or_b32 v203, v80, 4, 31
	v_cndmask_b32_e32 v185, v227, v87, vcc
	v_cmp_le_i32_e32 vcc, v203, v178
	v_cmp_gt_u32_e64 s[24:25], s33, v80
	v_or_b32_e32 v80, 17, v175
	s_and_b64 vcc, vcc, s[24:25]
	v_lshl_add_u32 v201, v80, 4, 31
	v_cndmask_b32_e32 v176, v227, v88, vcc
	v_cmp_le_i32_e32 vcc, v201, v178
	v_cmp_gt_u32_e64 s[6:7], s33, v80
	v_or_b32_e32 v80, 18, v175
	s_and_b64 vcc, vcc, s[6:7]
	v_lshl_or_b32 v191, v80, 4, 31
	v_cndmask_b32_e32 v180, v227, v89, vcc
	v_cmp_le_i32_e32 vcc, v191, v178
	v_cmp_gt_u32_e64 s[0:1], s33, v80
	v_or_b32_e32 v80, 19, v175
	s_and_b64 vcc, vcc, s[0:1]
	v_lshl_add_u32 v192, v80, 4, 31
	v_cmp_gt_u32_e64 s[2:3], s33, v80
	v_or_b32_e32 v80, 24, v175
	v_cndmask_b32_e32 v181, v227, v90, vcc
	v_cmp_le_i32_e32 vcc, v192, v178
	v_lshl_or_b32 v193, v80, 4, 31
	v_cmp_gt_u32_e64 s[4:5], s33, v80
	v_or_b32_e32 v80, 25, v175
	s_and_b64 vcc, vcc, s[2:3]
	v_lshl_add_u32 v194, v80, 4, 31
	v_cmp_gt_u32_e64 s[8:9], s33, v80
	v_or_b32_e32 v80, 26, v175
	v_cndmask_b32_e32 v182, v227, v91, vcc
	v_cmp_le_i32_e32 vcc, v193, v178
	v_lshl_or_b32 v196, v80, 4, 31
	v_cmp_gt_u32_e64 s[10:11], s33, v80
	v_or_b32_e32 v80, 27, v175
	s_and_b64 vcc, vcc, s[4:5]
	v_lshl_add_u32 v197, v80, 4, 31
	v_cmp_gt_u32_e64 s[12:13], s33, v80
	v_max_f32_e32 v80, v189, v189
	v_max_f32_e32 v81, v190, v190
	v_cndmask_b32_e32 v170, v227, v92, vcc
	v_cmp_le_i32_e32 vcc, v194, v178
	v_max_f32_e32 v80, v81, v80
	s_and_b64 vcc, vcc, s[8:9]
	v_max3_f32 v80, v80, v188, v187
	v_cndmask_b32_e32 v171, v227, v93, vcc
	v_cmp_le_i32_e32 vcc, v196, v178
	v_max3_f32 v80, v80, v186, v183
	s_and_b64 vcc, vcc, s[10:11]
	v_max3_f32 v80, v80, v184, v185
	v_cndmask_b32_e32 v174, v227, v94, vcc
	v_cmp_le_i32_e32 vcc, v197, v178
	v_max3_f32 v80, v80, v176, v180
	s_and_b64 vcc, vcc, s[12:13]
	v_max3_f32 v80, v80, v181, v182
	v_cndmask_b32_e32 v175, v227, v95, vcc
	v_max3_f32 v80, v80, v170, v171
	v_max3_f32 v80, v80, v174, v175
	v_mov_b32_e32 v81, v80
	s_nop 1
	v_permlane32_swap_b32 v80, v81
	s_waitcnt lgkmcnt(0)
	v_max_f32_e32 v81, v81, v81
	v_max_f32_e32 v80, v80, v81
	v_add_f32_e32 v81, 0x41000000, v160
	v_cmp_gt_f32_e32 vcc, v80, v81
	s_cbranch_vccz .LBB0_678
	s_nop 0
	v_cndmask_b32_e32 v81, v160, v80, vcc
	v_sub_f32_e32 v80, v160, v81
	v_exp_f32_e32 v80, v80
	v_mov_b32_e32 v160, v81
	v_mul_f32_e32 v14, v14, v80
	v_pk_mul_f32 v[78:79], v[78:79], v[80:81] op_sel_hi:[1,0]
	v_pk_mul_f32 v[76:77], v[76:77], v[80:81] op_sel_hi:[1,0]
	v_pk_mul_f32 v[74:75], v[74:75], v[80:81] op_sel_hi:[1,0]
	v_pk_mul_f32 v[72:73], v[72:73], v[80:81] op_sel_hi:[1,0]
	v_pk_mul_f32 v[70:71], v[70:71], v[80:81] op_sel_hi:[1,0]
	v_pk_mul_f32 v[68:69], v[68:69], v[80:81] op_sel_hi:[1,0]
	v_pk_mul_f32 v[66:67], v[66:67], v[80:81] op_sel_hi:[1,0]
	v_pk_mul_f32 v[64:65], v[64:65], v[80:81] op_sel_hi:[1,0]
	v_pk_mul_f32 v[62:63], v[62:63], v[80:81] op_sel_hi:[1,0]
	v_pk_mul_f32 v[60:61], v[60:61], v[80:81] op_sel_hi:[1,0]
	v_pk_mul_f32 v[58:59], v[58:59], v[80:81] op_sel_hi:[1,0]
	v_pk_mul_f32 v[56:57], v[56:57], v[80:81] op_sel_hi:[1,0]
	v_pk_mul_f32 v[54:55], v[54:55], v[80:81] op_sel_hi:[1,0]
	v_pk_mul_f32 v[52:53], v[52:53], v[80:81] op_sel_hi:[1,0]
	v_pk_mul_f32 v[50:51], v[50:51], v[80:81] op_sel_hi:[1,0]
	v_pk_mul_f32 v[48:49], v[48:49], v[80:81] op_sel_hi:[1,0]
; #define MFMA(a, b, c) __builtin_amdgcn_mfma_f32_32x32x16_f16(__builtin_bit_cast(h16x8, (a)), __builtin_bit_cast(h16x8, (b)), (c), 0, 0, 0)
; template <int MODE> ...
;     ...
; #pragma unroll
;           for (int ks = 0; ks < 4; ++ks) {
;             const bf16x8 a = *(const bf16x8*)(Kt + (kb * 32 + r) * LDK + ks * 16 + 8 * h);
;             Sn = MFMA(a, qf[nb][ks], Sn);
;           }
;           float sv[16];
;           const int t = qpos[nb];
;           bool sb = true;
;           if (MODE == M_SLC) sb = (((selb[nb] >> (key0 >> 6)) & 1ull) != 0ull);
;           if (domask) {
; #pragma unroll
;             for (int i = 0; i < 16; ++i) {
;               const int kk = kbase + (i & 3) + 8 * (i >> 2) + 4 * h;
;               bool valid;
;               if (MODE == M_FOX) valid = (kk <= t);
;               else if (MODE == M_CMP || MODE == M_CMP2) valid = (16 * kk + 31 <= t) && (kk < 255);
;               else if (MODE == M_SLC) valid = sb && (kk <= t);
;               else valid = (kk <= t) && (kk > t - 512);
;               sv[i] = valid ? Sn[i] : -INFINITY;
;             }
;           } else {
; #pragma unroll
;             for (int i = 0; i < 16; ++i) sv[i] = (MODE == M_SLC) ? (sb ? Sn[i] : -INFINITY) : Sn[i];
;           }
;           if (MODE == M_CMP2) {
; #pragma unroll
;             for (int a4 = 0; a4 < 4; ++a4) {
;               float pe[4];
; #pragma unroll
;               for (int e = 0; e < 4; ++e) pe[e] = __builtin_amdgcn_exp2f(sv[4 * a4 + e] - m[nb]) * linv[nb];
;               mainv[nb][a4] = pe[0] + pe[1] + pe[2] + 0.5f * pe[3];
;               spill[nb][a4] = 0.5f * pe[3];
;             }
;           } else {
;             float mx = sv[0];
; #pragma unroll
;             for (int i = 1; i < 16; ++i) mx = fmaxf(mx, sv[i]);
;             mx = fmaxf(mx, shx(mx, lane, 32));
;             if (__any(mx > m[nb] + 8.f)) {
;               const float mnew = (mx > m[nb] + 8.f) ? mx : m[nb];
;               const float alpha = __builtin_amdgcn_exp2f(m[nb] - mnew);
;               m[nb] = mnew;
;               l[nb] *= alpha;
; #pragma unroll
;               for (int i = 0; i < 16; ++i) { O[0][nb][i] *= alpha; O[1][nb][i] *= alpha; }
;             }
.LBB0_678:
	v_mfma_f32_32x32x16_f16 v[80:95], v[2:5], v[136:139], 0
	v_cmp_le_i32_e32 vcc, v195, v179
	s_and_b64 vcc, vcc, s[14:15]
	v_mfma_f32_32x32x16_f16 v[80:95], v[6:9], v[128:131], v[80:95]
	v_mfma_f32_32x32x16_f16 v[80:95], v[10:13], v[132:135], v[80:95]
	v_mfma_f32_32x32x16_f16 v[80:95], v[144:147], v[140:143], v[80:95]
	s_nop 11
	v_cndmask_b32_e32 v6, v227, v80, vcc
	v_cmp_le_i32_e32 vcc, v205, v179
	s_and_b64 vcc, vcc, s[28:29]
	v_max_f32_e32 v3, v6, v6
	v_cndmask_b32_e32 v7, v227, v81, vcc
	v_cmp_le_i32_e32 vcc, v202, v179
	s_and_b64 vcc, vcc, s[22:23]
	v_max_f32_e32 v2, v7, v7
	v_cndmask_b32_e32 v8, v227, v82, vcc
	v_cmp_le_i32_e32 vcc, v200, v179
	s_and_b64 vcc, vcc, s[20:21]
	v_max_f32_e32 v2, v3, v2
	v_cndmask_b32_e32 v9, v227, v83, vcc
	v_cmp_le_i32_e32 vcc, v199, v179
	s_and_b64 vcc, vcc, s[18:19]
	v_max3_f32 v2, v2, v8, v9
	v_cndmask_b32_e32 v80, v227, v84, vcc
	v_cmp_le_i32_e32 vcc, v198, v179
	s_and_b64 vcc, vcc, s[16:17]
	s_nop 0
	v_cndmask_b32_e32 v81, v227, v85, vcc
	v_cmp_le_i32_e32 vcc, v206, v179
	s_and_b64 vcc, vcc, s[30:31]
	v_max3_f32 v2, v2, v80, v81
	v_cndmask_b32_e32 v82, v227, v86, vcc
	v_cmp_le_i32_e32 vcc, v204, v179
	s_and_b64 vcc, vcc, s[26:27]
	s_nop 0
	v_cndmask_b32_e32 v83, v227, v87, vcc
	v_cmp_le_i32_e32 vcc, v203, v179
	s_and_b64 vcc, vcc, s[24:25]
	v_max3_f32 v2, v2, v82, v83
	v_cndmask_b32_e32 v84, v227, v88, vcc
	v_cmp_le_i32_e32 vcc, v201, v179
	s_and_b64 vcc, vcc, s[6:7]
	s_nop 0
	v_cndmask_b32_e32 v85, v227, v89, vcc
	v_cmp_le_i32_e32 vcc, v191, v179
	s_and_b64 vcc, vcc, s[0:1]
	v_max3_f32 v2, v2, v84, v85
	v_cndmask_b32_e32 v86, v227, v90, vcc
	v_cmp_le_i32_e32 vcc, v192, v179
	s_and_b64 vcc, vcc, s[2:3]
	s_nop 0
	v_cndmask_b32_e32 v87, v227, v91, vcc
	v_cmp_le_i32_e32 vcc, v193, v179
	s_and_b64 vcc, vcc, s[4:5]
	v_max3_f32 v2, v2, v86, v87
	v_cndmask_b32_e32 v88, v227, v92, vcc
	v_cmp_le_i32_e32 vcc, v194, v179
	s_and_b64 vcc, vcc, s[8:9]
	s_nop 0
	v_cndmask_b32_e32 v89, v227, v93, vcc
	v_cmp_le_i32_e32 vcc, v196, v179
	s_and_b64 vcc, vcc, s[10:11]
	v_max3_f32 v2, v2, v88, v89
	v_cndmask_b32_e32 v90, v227, v94, vcc
	v_cmp_le_i32_e32 vcc, v197, v179
	s_and_b64 vcc, vcc, s[12:13]
	s_nop 0
	v_cndmask_b32_e32 v91, v227, v95, vcc
	v_max3_f32 v2, v2, v90, v91
	v_mov_b32_e32 v3, v2
	s_nop 1
	v_permlane32_swap_b32 v2, v3
	s_waitcnt lgkmcnt(0)
	v_max_f32_e32 v3, v3, v3
	v_max_f32_e32 v2, v2, v3
	v_add_f32_e32 v3, 0x41000000, v159
	v_cmp_gt_f32_e32 vcc, v2, v3
	s_cbranch_vccz .LBB0_673
	s_nop 0
	v_cndmask_b32_e32 v3, v159, v2, vcc
	v_sub_f32_e32 v2, v159, v3
	v_exp_f32_e32 v2, v2
	v_mov_b32_e32 v159, v3
	v_mul_f32_e32 v161, v161, v2
	v_pk_mul_f32 v[46:47], v[46:47], v[2:3] op_sel_hi:[1,0]
	v_pk_mul_f32 v[44:45], v[44:45], v[2:3] op_sel_hi:[1,0]
	v_pk_mul_f32 v[42:43], v[42:43], v[2:3] op_sel_hi:[1,0]
	v_pk_mul_f32 v[40:41], v[40:41], v[2:3] op_sel_hi:[1,0]
	v_pk_mul_f32 v[38:39], v[38:39], v[2:3] op_sel_hi:[1,0]
	v_pk_mul_f32 v[36:37], v[36:37], v[2:3] op_sel_hi:[1,0]
	v_pk_mul_f32 v[34:35], v[34:35], v[2:3] op_sel_hi:[1,0]
	v_pk_mul_f32 v[32:33], v[32:33], v[2:3] op_sel_hi:[1,0]
	v_pk_mul_f32 v[30:31], v[30:31], v[2:3] op_sel_hi:[1,0]
	v_pk_mul_f32 v[28:29], v[28:29], v[2:3] op_sel_hi:[1,0]
	v_pk_mul_f32 v[26:27], v[26:27], v[2:3] op_sel_hi:[1,0]
	v_pk_mul_f32 v[24:25], v[24:25], v[2:3] op_sel_hi:[1,0]
	v_pk_mul_f32 v[22:23], v[22:23], v[2:3] op_sel_hi:[1,0]
	v_pk_mul_f32 v[20:21], v[20:21], v[2:3] op_sel_hi:[1,0]
	v_pk_mul_f32 v[18:19], v[18:19], v[2:3] op_sel_hi:[1,0]
	v_pk_mul_f32 v[16:17], v[16:17], v[2:3] op_sel_hi:[1,0]
	s_branch .LBB0_673

; template <int MODE> ...
;     ...
;             float mx = sv[0];
; #pragma unroll
;             for (int i = 1; i < 16; ++i) mx = fmaxf(mx, sv[i]);
;             mx = fmaxf(mx, shx(mx, lane, 32));
;             if (__any(mx > m[nb] + 8.f)) {
;               const float mnew = (mx > m[nb] + 8.f) ? mx : m[nb];
;               const float alpha = __builtin_amdgcn_exp2f(m[nb] - mnew);
;               m[nb] = mnew;
;               l[nb] *= alpha;
; #pragma unroll
;               for (int i = 0; i < 16; ++i) { O[0][nb][i] *= alpha; O[1][nb][i] *= alpha; }
;             }
.LBB0_736:
	s_nop 6
	v_max_f32_e32 v96, v81, v81
	v_max_f32_e32 v97, v80, v80
	v_max_f32_e32 v96, v97, v96
	v_max3_f32 v96, v96, v82, v83
	v_max3_f32 v96, v96, v84, v85
	v_max3_f32 v96, v96, v86, v87
	v_max3_f32 v96, v96, v88, v89
	v_max3_f32 v96, v96, v90, v91
	v_cndmask_b32_e64 v95, v227, v111, s[12:13]
	v_max3_f32 v96, v96, v92, v93
	v_max3_f32 v96, v96, v94, v95
	v_mov_b32_e32 v97, v96
	s_nop 1
	v_permlane32_swap_b32 v96, v97
	s_waitcnt lgkmcnt(0)
	v_max_f32_e32 v97, v97, v97
	v_max_f32_e32 v96, v96, v97
	v_add_f32_e32 v97, 0x41000000, v15
	v_cmp_gt_f32_e32 vcc, v96, v97
	s_cbranch_vccz .LBB0_738
	s_nop 0
	v_cndmask_b32_e32 v97, v15, v96, vcc
	v_sub_f32_e32 v15, v15, v97
	v_exp_f32_e32 v96, v15
	v_mov_b32_e32 v15, v97
	v_mul_f32_e32 v14, v14, v96
	v_pk_mul_f32 v[78:79], v[78:79], v[96:97] op_sel_hi:[1,0]
	v_pk_mul_f32 v[76:77], v[76:77], v[96:97] op_sel_hi:[1,0]
	v_pk_mul_f32 v[74:75], v[74:75], v[96:97] op_sel_hi:[1,0]
	v_pk_mul_f32 v[72:73], v[72:73], v[96:97] op_sel_hi:[1,0]
	v_pk_mul_f32 v[70:71], v[70:71], v[96:97] op_sel_hi:[1,0]
	v_pk_mul_f32 v[68:69], v[68:69], v[96:97] op_sel_hi:[1,0]
	v_pk_mul_f32 v[66:67], v[66:67], v[96:97] op_sel_hi:[1,0]
	v_pk_mul_f32 v[64:65], v[64:65], v[96:97] op_sel_hi:[1,0]
	v_pk_mul_f32 v[62:63], v[62:63], v[96:97] op_sel_hi:[1,0]
	v_pk_mul_f32 v[60:61], v[60:61], v[96:97] op_sel_hi:[1,0]
	v_pk_mul_f32 v[58:59], v[58:59], v[96:97] op_sel_hi:[1,0]
	v_pk_mul_f32 v[56:57], v[56:57], v[96:97] op_sel_hi:[1,0]
	v_pk_mul_f32 v[54:55], v[54:55], v[96:97] op_sel_hi:[1,0]
	v_pk_mul_f32 v[52:53], v[52:53], v[96:97] op_sel_hi:[1,0]
	v_pk_mul_f32 v[50:51], v[50:51], v[96:97] op_sel_hi:[1,0]
	v_pk_mul_f32 v[48:49], v[48:49], v[96:97] op_sel_hi:[1,0]

; template <int MODE> ...
;     ...
;             float mx = sv[0];
; #pragma unroll
;             for (int i = 1; i < 16; ++i) mx = fmaxf(mx, sv[i]);
;             mx = fmaxf(mx, shx(mx, lane, 32));
;             if (__any(mx > m[nb] + 8.f)) {
;               const float mnew = (mx > m[nb] + 8.f) ? mx : m[nb];
;               const float alpha = __builtin_amdgcn_exp2f(m[nb] - mnew);
;               m[nb] = mnew;
;               l[nb] *= alpha;
; #pragma unroll
;               for (int i = 0; i < 16; ++i) { O[0][nb][i] *= alpha; O[1][nb][i] *= alpha; }
;             }
.LBB0_742:
	v_max_f32_e32 v2, v81, v81
	v_max_f32_e32 v3, v80, v80
	v_max_f32_e32 v2, v3, v2
	v_max3_f32 v2, v2, v82, v83
	v_max3_f32 v2, v2, v84, v85
	v_max3_f32 v2, v2, v86, v87
	v_max3_f32 v2, v2, v88, v89
	v_max3_f32 v2, v2, v90, v91
	v_cndmask_b32_e64 v95, v227, v111, s[10:11]
	v_max3_f32 v2, v2, v92, v93
	v_max3_f32 v2, v2, v94, v95
	v_mov_b32_e32 v3, v2
	s_nop 1
	v_permlane32_swap_b32 v2, v3
	s_waitcnt lgkmcnt(0)
	v_max_f32_e32 v3, v3, v3
	v_max_f32_e32 v2, v2, v3
	v_add_f32_e32 v3, 0x41000000, v205
	v_cmp_gt_f32_e32 vcc, v2, v3
	s_cbranch_vccz .LBB0_729
	s_nop 0
	v_cndmask_b32_e32 v3, v205, v2, vcc
	v_sub_f32_e32 v2, v205, v3
	v_exp_f32_e32 v2, v2
	v_mov_b32_e32 v205, v3
	v_mul_f32_e32 v180, v180, v2
	v_pk_mul_f32 v[46:47], v[46:47], v[2:3] op_sel_hi:[1,0]
	v_pk_mul_f32 v[44:45], v[44:45], v[2:3] op_sel_hi:[1,0]
	v_pk_mul_f32 v[42:43], v[42:43], v[2:3] op_sel_hi:[1,0]
	v_pk_mul_f32 v[40:41], v[40:41], v[2:3] op_sel_hi:[1,0]
	v_pk_mul_f32 v[38:39], v[38:39], v[2:3] op_sel_hi:[1,0]
	v_pk_mul_f32 v[36:37], v[36:37], v[2:3] op_sel_hi:[1,0]
	v_pk_mul_f32 v[34:35], v[34:35], v[2:3] op_sel_hi:[1,0]
	v_pk_mul_f32 v[32:33], v[32:33], v[2:3] op_sel_hi:[1,0]
	v_pk_mul_f32 v[30:31], v[30:31], v[2:3] op_sel_hi:[1,0]
	v_pk_mul_f32 v[28:29], v[28:29], v[2:3] op_sel_hi:[1,0]
	v_pk_mul_f32 v[26:27], v[26:27], v[2:3] op_sel_hi:[1,0]
	v_pk_mul_f32 v[24:25], v[24:25], v[2:3] op_sel_hi:[1,0]
	v_pk_mul_f32 v[22:23], v[22:23], v[2:3] op_sel_hi:[1,0]
	v_pk_mul_f32 v[20:21], v[20:21], v[2:3] op_sel_hi:[1,0]
	v_pk_mul_f32 v[18:19], v[18:19], v[2:3] op_sel_hi:[1,0]
	v_pk_mul_f32 v[16:17], v[16:17], v[2:3] op_sel_hi:[1,0]
	s_branch .LBB0_729

; template <int MODE> ...
;     ...
;             float mx = sv[0];
; #pragma unroll
;             for (int i = 1; i < 16; ++i) mx = fmaxf(mx, sv[i]);
;             mx = fmaxf(mx, shx(mx, lane, 32));
;             if (__any(mx > m[nb] + 8.f)) {
;               const float mnew = (mx > m[nb] + 8.f) ? mx : m[nb];
;               const float alpha = __builtin_amdgcn_exp2f(m[nb] - mnew);
;               m[nb] = mnew;
;               l[nb] *= alpha;
; #pragma unroll
;               for (int i = 0; i < 16; ++i) { O[0][nb][i] *= alpha; O[1][nb][i] *= alpha; }
;             }
.LBB0_758:
	s_nop 9
	v_max_f32_e32 v96, v81, v81
	v_max_f32_e32 v97, v80, v80
	v_max_f32_e32 v96, v97, v96
	v_max3_f32 v96, v96, v82, v83
	v_max3_f32 v96, v96, v84, v85
	v_max3_f32 v96, v96, v86, v87
	v_max3_f32 v96, v96, v88, v89
	v_max3_f32 v96, v96, v90, v91
	v_max3_f32 v96, v96, v92, v93
	v_max3_f32 v96, v96, v94, v95
	v_mov_b32_e32 v97, v96
	s_nop 1
	v_permlane32_swap_b32 v96, v97
	s_waitcnt lgkmcnt(0)
	v_max_f32_e32 v97, v97, v97
	v_max_f32_e32 v96, v96, v97
	v_add_f32_e32 v97, 0x41000000, v15
	v_cmp_gt_f32_e32 vcc, v96, v97
	s_cbranch_vccz .LBB0_760
	s_nop 0
	v_cndmask_b32_e32 v97, v15, v96, vcc
	v_sub_f32_e32 v15, v15, v97
	v_exp_f32_e32 v96, v15
	v_mov_b32_e32 v15, v97
	v_mul_f32_e32 v14, v14, v96
	v_pk_mul_f32 v[78:79], v[78:79], v[96:97] op_sel_hi:[1,0]
	v_pk_mul_f32 v[76:77], v[76:77], v[96:97] op_sel_hi:[1,0]
	v_pk_mul_f32 v[74:75], v[74:75], v[96:97] op_sel_hi:[1,0]
	v_pk_mul_f32 v[72:73], v[72:73], v[96:97] op_sel_hi:[1,0]
	v_pk_mul_f32 v[70:71], v[70:71], v[96:97] op_sel_hi:[1,0]
	v_pk_mul_f32 v[68:69], v[68:69], v[96:97] op_sel_hi:[1,0]
	v_pk_mul_f32 v[66:67], v[66:67], v[96:97] op_sel_hi:[1,0]
	v_pk_mul_f32 v[64:65], v[64:65], v[96:97] op_sel_hi:[1,0]
	v_pk_mul_f32 v[62:63], v[62:63], v[96:97] op_sel_hi:[1,0]
	v_pk_mul_f32 v[60:61], v[60:61], v[96:97] op_sel_hi:[1,0]
	v_pk_mul_f32 v[58:59], v[58:59], v[96:97] op_sel_hi:[1,0]
	v_pk_mul_f32 v[56:57], v[56:57], v[96:97] op_sel_hi:[1,0]
	v_pk_mul_f32 v[54:55], v[54:55], v[96:97] op_sel_hi:[1,0]
	v_pk_mul_f32 v[52:53], v[52:53], v[96:97] op_sel_hi:[1,0]
	v_pk_mul_f32 v[50:51], v[50:51], v[96:97] op_sel_hi:[1,0]
	v_pk_mul_f32 v[48:49], v[48:49], v[96:97] op_sel_hi:[1,0]

; template <int MODE> ...
;     ...
;             float mx = sv[0];
; #pragma unroll
;             for (int i = 1; i < 16; ++i) mx = fmaxf(mx, sv[i]);
;             mx = fmaxf(mx, shx(mx, lane, 32));
;             if (__any(mx > m[nb] + 8.f)) {
;               const float mnew = (mx > m[nb] + 8.f) ? mx : m[nb];
;               const float alpha = __builtin_amdgcn_exp2f(m[nb] - mnew);
;               m[nb] = mnew;
;               l[nb] *= alpha;
; #pragma unroll
;               for (int i = 0; i < 16; ++i) { O[0][nb][i] *= alpha; O[1][nb][i] *= alpha; }
;             }
.LBB0_762:
	s_nop 10
	v_max_f32_e32 v2, v97, v97
	v_max_f32_e32 v3, v96, v96
	v_max_f32_e32 v2, v3, v2
	v_max3_f32 v2, v2, v98, v99
	v_max3_f32 v2, v2, v100, v101
	v_max3_f32 v2, v2, v102, v103
	v_max3_f32 v2, v2, v104, v105
	v_max3_f32 v2, v2, v106, v107
	v_max3_f32 v2, v2, v108, v109
	v_max3_f32 v2, v2, v110, v111
	v_mov_b32_e32 v3, v2
	s_nop 1
	v_permlane32_swap_b32 v2, v3
	s_waitcnt lgkmcnt(0)
	v_max_f32_e32 v3, v3, v3
	v_max_f32_e32 v2, v2, v3
	v_add_f32_e32 v3, 0x41000000, v188
	v_cmp_gt_f32_e32 vcc, v2, v3
	s_cbranch_vccz .LBB0_753
	s_nop 0
	v_cndmask_b32_e32 v3, v188, v2, vcc
	v_sub_f32_e32 v2, v188, v3
	v_exp_f32_e32 v2, v2
	v_mov_b32_e32 v188, v3
	v_mul_f32_e32 v164, v164, v2
	v_pk_mul_f32 v[46:47], v[46:47], v[2:3] op_sel_hi:[1,0]
	v_pk_mul_f32 v[44:45], v[44:45], v[2:3] op_sel_hi:[1,0]
	v_pk_mul_f32 v[42:43], v[42:43], v[2:3] op_sel_hi:[1,0]
	v_pk_mul_f32 v[40:41], v[40:41], v[2:3] op_sel_hi:[1,0]
	v_pk_mul_f32 v[38:39], v[38:39], v[2:3] op_sel_hi:[1,0]
	v_pk_mul_f32 v[36:37], v[36:37], v[2:3] op_sel_hi:[1,0]
	v_pk_mul_f32 v[34:35], v[34:35], v[2:3] op_sel_hi:[1,0]
	v_pk_mul_f32 v[32:33], v[32:33], v[2:3] op_sel_hi:[1,0]
	v_pk_mul_f32 v[30:31], v[30:31], v[2:3] op_sel_hi:[1,0]
	v_pk_mul_f32 v[28:29], v[28:29], v[2:3] op_sel_hi:[1,0]
	v_pk_mul_f32 v[26:27], v[26:27], v[2:3] op_sel_hi:[1,0]
	v_pk_mul_f32 v[24:25], v[24:25], v[2:3] op_sel_hi:[1,0]
	v_pk_mul_f32 v[22:23], v[22:23], v[2:3] op_sel_hi:[1,0]
	v_pk_mul_f32 v[20:21], v[20:21], v[2:3] op_sel_hi:[1,0]
	v_pk_mul_f32 v[18:19], v[18:19], v[2:3] op_sel_hi:[1,0]
	v_pk_mul_f32 v[16:17], v[16:17], v[2:3] op_sel_hi:[1,0]
	s_branch .LBB0_753
